# v25 + attention loop tail: slot/counter/address updates moved in front of the closing barrier; merge chain scheduler fast path for sub>0
# speedup vs baseline: 1.0023x; 1.0023x over previous
; #define WAIT_BAR(N) asm volatile("s_waitcnt vmcnt(" #N ") lgkmcnt(0)\n\ts_barrier":::"memory")
;   #define RESC() do{ if(resc){ asm volatile("s_waitcnt lgkmcnt(0)":::"memory"); \
;       _Pragma("unroll") for(int d_=0;d_<2;++d_) _Pragma("unroll") for(int r=0;r<16;++r)o[d_][r]*=wsf[crow(r,hi)]; } }while(0)
;   #define ROT() do{sl_prev=sl_cur;sl_cur=sl_next;sl_next=(sl_next==(NSLOT-1)*SLOTB)?0:sl_next+SLOTB;}while(0)
; template<int THRL,int L,int NT> __device__ __forceinline__ void attn_unit(long rowbase,int kvh,int qblk,const bf16*Q,const bf16*__restrict__ K,const bf16*__restrict__ V,bf16*O,char*shm,const int tid){
;     ...
;   for(;t+5<NT;t+=2){
;     STEP(pB0,pB1,pA0,pA1,t,true,true,true);     WAIT_BAR(2); RESC(); ROT();
;     STEP(pA0,pA1,pB0,pB1,t+1,true,true,true);   WAIT_BAR(2); RESC(); ROT();
.LBB0_882:
	s_waitcnt lgkmcnt(14)
	v_mfma_f32_32x32x16_bf16 v[2:17], v[158:161], v[126:129], v[2:17]
	v_exp_f32_e32 v66, v66
	v_exp_f32_e32 v67, v67
	v_exp_f32_e32 v68, v68
	v_exp_f32_e32 v69, v69
	s_waitcnt lgkmcnt(12)
	v_mfma_f32_32x32x16_bf16 v[18:33], v[158:161], v[122:125], v[18:33]
	v_exp_f32_e32 v70, v70
	v_exp_f32_e32 v71, v71
	v_exp_f32_e32 v72, v72
	v_exp_f32_e32 v73, v73
	v_add_u32_e32 v90, s65, v211
	ds_read_b128 v[82:85], v90
	ds_read_b128 v[170:173], v90 offset:512
	s_waitcnt lgkmcnt(12)
	v_mfma_f32_32x32x16_bf16 v[2:17], v[154:157], v[118:121], v[2:17]
	v_exp_f32_e32 v74, v74
	v_exp_f32_e32 v75, v75
	v_exp_f32_e32 v76, v76
	v_exp_f32_e32 v77, v77
	ds_read_b128 v[166:169], v90 offset:2048
	ds_read_b128 v[162:165], v90 offset:2560
	s_waitcnt lgkmcnt(12)
	v_mfma_f32_32x32x16_bf16 v[18:33], v[154:157], v[114:117], v[18:33]
	v_exp_f32_e32 v78, v78
	v_exp_f32_e32 v79, v79
	v_exp_f32_e32 v80, v80
	v_exp_f32_e32 v81, v81
	ds_read_b128 v[126:129], v90 offset:4096
	ds_read_b128 v[122:125], v90 offset:4608
	s_waitcnt lgkmcnt(12)
	v_mfma_f32_32x32x16_bf16 v[2:17], v[150:153], v[106:109], v[2:17]
	v_exp_f32_e32 v50, v50
	v_exp_f32_e32 v51, v51
	v_exp_f32_e32 v52, v52
	v_exp_f32_e32 v53, v53
	ds_read_b128 v[118:121], v90 offset:6144
	ds_read_b128 v[114:117], v90 offset:6656
	s_waitcnt lgkmcnt(12)
	v_mfma_f32_32x32x16_bf16 v[18:33], v[150:153], v[102:105], v[18:33]
	v_exp_f32_e32 v54, v54
	v_exp_f32_e32 v55, v55
	v_exp_f32_e32 v56, v56
	v_exp_f32_e32 v57, v57
	s_waitcnt lgkmcnt(10)
	v_mfma_f32_32x32x16_bf16 v[2:17], v[146:149], v[98:101], v[2:17]
	v_exp_f32_e32 v58, v58
	v_exp_f32_e32 v59, v59
	v_exp_f32_e32 v60, v60
	v_exp_f32_e32 v61, v61
	s_waitcnt lgkmcnt(8)
	v_mfma_f32_32x32x16_bf16 v[18:33], v[146:149], v[86:89], v[18:33]
	v_exp_f32_e32 v62, v62
	v_exp_f32_e32 v63, v63
	v_exp_f32_e32 v64, v64
	v_exp_f32_e32 v65, v65
	s_add_i32 s15, s65, 0x2000
	s_cmpk_lg_i32 s65, 0x4000
	s_cselect_b32 s15, s15, 0
	s_add_i32 s95, s95, 2
	v_lshl_add_u64 v[196:197], v[196:197], 0, s[28:29]
	s_waitcnt vmcnt(2) lgkmcnt(0)
	s_barrier
	s_andn2_b64 vcc, exec, s[60:61]
	s_cbranch_vccnz .LBB0_884
	s_waitcnt lgkmcnt(0)
	v_add_u32_e32 v98, s92, v212
	ds_read_b128 v[86:89], v98 offset:49248
	ds_read_b128 v[90:93], v98 offset:49216
	ds_read_b128 v[94:97], v98 offset:49184
	ds_read_b128 v[98:101], v98 offset:49152
	s_waitcnt lgkmcnt(3)
	v_pk_mul_f32 v[14:15], v[14:15], v[86:87]
	s_waitcnt lgkmcnt(2)
	v_pk_mul_f32 v[10:11], v[10:11], v[90:91]
	s_waitcnt lgkmcnt(1)
	v_pk_mul_f32 v[6:7], v[6:7], v[94:95]
	v_pk_mul_f32 v[16:17], v[16:17], v[88:89]
	v_pk_mul_f32 v[12:13], v[12:13], v[92:93]
	v_pk_mul_f32 v[8:9], v[8:9], v[96:97]
	s_waitcnt lgkmcnt(0)
	v_pk_mul_f32 v[4:5], v[4:5], v[100:101]
	v_pk_mul_f32 v[2:3], v[2:3], v[98:99]
	v_pk_mul_f32 v[30:31], v[30:31], v[86:87]
	v_pk_mul_f32 v[26:27], v[26:27], v[90:91]
	v_pk_mul_f32 v[22:23], v[22:23], v[94:95]
	v_pk_mul_f32 v[32:33], v[32:33], v[88:89]
	v_pk_mul_f32 v[28:29], v[28:29], v[92:93]
	v_pk_mul_f32 v[24:25], v[24:25], v[96:97]
	v_pk_mul_f32 v[20:21], v[20:21], v[100:101]
	v_pk_mul_f32 v[18:19], v[18:19], v[98:99]
.LBB0_884:
	s_cmp_gt_u32 s95, 25
	s_cbranch_scc1 .LBB0_892
	s_mov_b32 s96, s18
	s_mov_b32 s64, s65
	s_mov_b32 s18, s15
	s_branch .LBB0_878

; #define WAIT_BAR(N) asm volatile("s_waitcnt vmcnt(" #N ") lgkmcnt(0)\n\ts_barrier":::"memory")
;   #define RESC() do{ if(resc){ asm volatile("s_waitcnt lgkmcnt(0)":::"memory"); \
;       _Pragma("unroll") for(int d_=0;d_<2;++d_) _Pragma("unroll") for(int r=0;r<16;++r)o[d_][r]*=wsf[crow(r,hi)]; } }while(0)
;   #define ROT() do{sl_prev=sl_cur;sl_cur=sl_next;sl_next=(sl_next==(NSLOT-1)*SLOTB)?0:sl_next+SLOTB;}while(0)
; template<int THRL,int L,int NT> __device__ __forceinline__ void attn_unit(long rowbase,int kvh,int qblk,const bf16*Q,const bf16*__restrict__ K,const bf16*__restrict__ V,bf16*O,char*shm,const int tid){
;     ...
;   for(;t+5<NT;t+=2){
;     STEP(pB0,pB1,pA0,pA1,t,true,true,true);     WAIT_BAR(2); RESC(); ROT();
;     STEP(pA0,pA1,pB0,pB1,t+1,true,true,true);   WAIT_BAR(2); RESC(); ROT();
.LBB0_923:
	s_waitcnt lgkmcnt(14)
	v_mfma_f32_32x32x16_bf16 v[2:17], v[158:161], v[126:129], v[2:17]
	v_exp_f32_e32 v66, v66
	v_exp_f32_e32 v67, v67
	v_exp_f32_e32 v68, v68
	v_exp_f32_e32 v69, v69
	s_waitcnt lgkmcnt(12)
	v_mfma_f32_32x32x16_bf16 v[18:33], v[158:161], v[122:125], v[18:33]
	v_exp_f32_e32 v70, v70
	v_exp_f32_e32 v71, v71
	v_exp_f32_e32 v72, v72
	v_exp_f32_e32 v73, v73
	v_add_u32_e32 v90, s65, v210
	ds_read_b128 v[82:85], v90
	ds_read_b128 v[170:173], v90 offset:512
	s_waitcnt lgkmcnt(12)
	v_mfma_f32_32x32x16_bf16 v[2:17], v[154:157], v[118:121], v[2:17]
	v_exp_f32_e32 v74, v74
	v_exp_f32_e32 v75, v75
	v_exp_f32_e32 v76, v76
	v_exp_f32_e32 v77, v77
	ds_read_b128 v[166:169], v90 offset:2048
	ds_read_b128 v[162:165], v90 offset:2560
	s_waitcnt lgkmcnt(12)
	v_mfma_f32_32x32x16_bf16 v[18:33], v[154:157], v[114:117], v[18:33]
	v_exp_f32_e32 v78, v78
	v_exp_f32_e32 v79, v79
	v_exp_f32_e32 v80, v80
	v_exp_f32_e32 v81, v81
	ds_read_b128 v[126:129], v90 offset:4096
	ds_read_b128 v[122:125], v90 offset:4608
	s_waitcnt lgkmcnt(12)
	v_mfma_f32_32x32x16_bf16 v[2:17], v[150:153], v[106:109], v[2:17]
	v_exp_f32_e32 v50, v50
	v_exp_f32_e32 v51, v51
	v_exp_f32_e32 v52, v52
	v_exp_f32_e32 v53, v53
	ds_read_b128 v[118:121], v90 offset:6144
	ds_read_b128 v[114:117], v90 offset:6656
	s_waitcnt lgkmcnt(12)
	v_mfma_f32_32x32x16_bf16 v[18:33], v[150:153], v[102:105], v[18:33]
	v_exp_f32_e32 v54, v54
	v_exp_f32_e32 v55, v55
	v_exp_f32_e32 v56, v56
	v_exp_f32_e32 v57, v57
	s_waitcnt lgkmcnt(10)
	v_mfma_f32_32x32x16_bf16 v[2:17], v[146:149], v[98:101], v[2:17]
	v_exp_f32_e32 v58, v58
	v_exp_f32_e32 v59, v59
	v_exp_f32_e32 v60, v60
	v_exp_f32_e32 v61, v61
	s_waitcnt lgkmcnt(8)
	v_mfma_f32_32x32x16_bf16 v[18:33], v[146:149], v[86:89], v[18:33]
	v_exp_f32_e32 v62, v62
	v_exp_f32_e32 v63, v63
	v_exp_f32_e32 v64, v64
	v_exp_f32_e32 v65, v65
	s_add_i32 s15, s65, 0x2000
	s_cmpk_lg_i32 s65, 0x4000
	s_cselect_b32 s15, s15, 0
	s_add_i32 s94, s94, 2
	v_lshl_add_u64 v[196:197], v[196:197], 0, s[28:29]
	s_waitcnt vmcnt(2) lgkmcnt(0)
	s_barrier
	s_andn2_b64 vcc, exec, s[60:61]
	s_cbranch_vccnz .LBB0_925
	s_waitcnt lgkmcnt(0)
	v_add_u32_e32 v98, s92, v211
	ds_read_b128 v[86:89], v98 offset:49248
	ds_read_b128 v[90:93], v98 offset:49216
	ds_read_b128 v[94:97], v98 offset:49184
	ds_read_b128 v[98:101], v98 offset:49152
	s_waitcnt lgkmcnt(3)
	v_pk_mul_f32 v[14:15], v[14:15], v[86:87]
	s_waitcnt lgkmcnt(2)
	v_pk_mul_f32 v[10:11], v[10:11], v[90:91]
	s_waitcnt lgkmcnt(1)
	v_pk_mul_f32 v[6:7], v[6:7], v[94:95]
	v_pk_mul_f32 v[16:17], v[16:17], v[88:89]
	v_pk_mul_f32 v[12:13], v[12:13], v[92:93]
	v_pk_mul_f32 v[8:9], v[8:9], v[96:97]
	s_waitcnt lgkmcnt(0)
	v_pk_mul_f32 v[4:5], v[4:5], v[100:101]
	v_pk_mul_f32 v[2:3], v[2:3], v[98:99]
	v_pk_mul_f32 v[30:31], v[30:31], v[86:87]
	v_pk_mul_f32 v[26:27], v[26:27], v[90:91]
	v_pk_mul_f32 v[22:23], v[22:23], v[94:95]
	v_pk_mul_f32 v[32:33], v[32:33], v[88:89]
	v_pk_mul_f32 v[28:29], v[28:29], v[92:93]
	v_pk_mul_f32 v[24:25], v[24:25], v[96:97]
	v_pk_mul_f32 v[20:21], v[20:21], v[100:101]
	v_pk_mul_f32 v[18:19], v[18:19], v[98:99]
.LBB0_925:
	s_cmp_gt_u32 s94, 57
	s_cbranch_scc1 .LBB0_933
	s_mov_b32 s18, s95
	s_mov_b32 s64, s65
	s_mov_b32 s95, s15
	s_branch .LBB0_919

;     __host__ __device__ bool next(int i, Unit& u) const {
;         const long L = (long)i * G + c; if (L >= nwg) return false;
;         int wgid = (int)L; { const int q = nwg / NXCD, r = nwg % NXCD, xcd = wgid % NXCD, off = wgid / NXCD; wgid = (xcd < r ? xcd * (q + 1) : r * (q + 1) + (xcd - r) * q) + off; }
;         const int nig = WGM * nN, gid = wgid / nig, fm = gid * WGM, gsz = (nM - fm) < WGM ? (nM - fm) : WGM;
;         u.pm = fm + ((wgid % nig) % gsz); u.pn = (wgid % nig) / gsz; u.sub = 0; return true;
;     __device__ __forceinline__ bool next(int i, pg8::Unit& u) const { if (!base.next(i >> 2, u)) return false; u.sub = i & 3; return true; }
.LBB0_1093:
	ds_read_b128 v[130:133], v139
	ds_read_b128 v[134:137], v139 offset:1024
	ds_read_b128 v[162:165], v139 offset:2048
	ds_read_b128 v[166:169], v139 offset:3072
	ds_read_b128 v[176:179], v173
	ds_read_b128 v[180:183], v173 offset:1024
	ds_read_b128 v[184:187], v173 offset:2048
	ds_read_b128 v[192:195], v173 offset:3072
	ds_read_b128 v[196:199], v174
	ds_read_b128 v[200:203], v174 offset:1024
	ds_read_b128 v[204:207], v174 offset:2048
	ds_read_b128 v[208:211], v174 offset:3072
	ds_read_b128 v[212:215], v174 offset:4096
	ds_read_b128 v[216:219], v174 offset:5120
	ds_read_b128 v[220:223], v174 offset:6144
	ds_read_b128 v[224:227], v174 offset:7168
	s_add_i32 s94, s94, 1
	s_lshr_b32 s0, s94, 2
	s_mul_hi_i32 s1, s0, s64
	s_mul_i32 s0, s0, s64
	s_add_u32 s2, s0, s8
	s_addc_u32 s3, s1, s9
	v_cmp_gt_i64_e32 vcc, s[2:3], v[160:161]
	v_cmp_lt_i64_e64 s[0:1], s[2:3], v[158:159]
	s_cbranch_vccnz .LBB0_1095
	s_and_b32 s95, s94, 3
	s_cmp_eq_u32 s95, 0
	s_cbranch_scc1 .Lmsf0
	s_mov_b32 s48, s4
	s_mov_b32 s50, s54
	s_branch .LBB0_1095
.Lmsf0:
	s_ashr_i32 s3, s2, 31
	s_lshr_b32 s3, s3, 29
	s_add_i32 s3, s2, s3
	s_ashr_i32 s5, s3, 3
	s_and_b32 s3, s3, -8
	s_sub_i32 s2, s2, s3
	s_cmp_lt_i32 s2, 0
	s_cselect_b32 s3, s85, 0x61
	s_mul_i32 s2, s3, s2
	s_add_i32 s2, s2, s5
	s_ashr_i32 s3, s2, 31
	s_lshr_b32 s3, s3, 27
	s_add_i32 s3, s2, s3
	s_ashr_i32 s5, s3, 5
	s_lshl_b32 s5, s5, 3
	s_sub_i32 s15, 0xc2, s5
	s_min_i32 s15, s15, 8
	s_abs_i32 s18, s15
	v_cvt_f32_u32_e32 v2, s18
	s_sub_i32 s48, 0, s18
	s_andn2_b32 s3, s3, 31
	s_sub_i32 s2, s2, s3
	v_rcp_iflag_f32_e32 v2, v2
	s_abs_i32 s3, s2
	s_xor_b32 s19, s2, s15
	s_ashr_i32 s19, s19, 31
	v_mul_f32_e32 v2, 0x4f7ffffe, v2
	v_cvt_u32_f32_e32 v2, v2
	s_nop 0
	v_readfirstlane_b32 s49, v2
	s_mul_i32 s48, s48, s49
	s_mul_hi_u32 s48, s49, s48
	s_add_i32 s49, s49, s48
	s_mul_hi_u32 s48, s3, s49
	s_mul_i32 s49, s48, s18
	s_sub_i32 s3, s3, s49
	s_add_i32 s50, s48, 1
	s_sub_i32 s49, s3, s18
	s_cmp_ge_u32 s3, s18
	s_cselect_b32 s48, s50, s48
	s_cselect_b32 s3, s49, s3
	s_add_i32 s49, s48, 1
	s_cmp_ge_u32 s3, s18
	s_cselect_b32 s3, s49, s48
	s_xor_b32 s3, s3, s19
	s_sub_i32 s48, s3, s19
	s_mul_i32 s3, s48, s15
	s_sub_i32 s2, s2, s3
	s_add_i32 s50, s2, s5
	s_and_b32 s95, s94, 3

; #define WAIT_BAR(N) asm volatile("s_waitcnt vmcnt(" #N ") lgkmcnt(0)\n\ts_barrier":::"memory")
;   #define RESC() do{ if(resc){ asm volatile("s_waitcnt lgkmcnt(0)":::"memory"); \
;       _Pragma("unroll") for(int d_=0;d_<2;++d_) _Pragma("unroll") for(int r=0;r<16;++r)o[d_][r]*=wsf[crow(r,hi)]; } }while(0)
;   #define ROT() do{sl_prev=sl_cur;sl_cur=sl_next;sl_next=(sl_next==(NSLOT-1)*SLOTB)?0:sl_next+SLOTB;}while(0)
; template<int THRL,int L,int NT> __device__ __forceinline__ void attn_unit(long rowbase,int kvh,int qblk,const bf16*Q,const bf16*__restrict__ K,const bf16*__restrict__ V,bf16*O,char*shm,const int tid){
;     ...
;   for(;t+5<NT;t+=2){
;     STEP(pB0,pB1,pA0,pA1,t,true,true,true);     WAIT_BAR(2); RESC(); ROT();
;     STEP(pA0,pA1,pB0,pB1,t+1,true,true,true);   WAIT_BAR(2); RESC(); ROT();
.LBB0_2483:
	s_cmp_gt_u32 s95, 25
	s_cbranch_scc1 .LBB0_2491
	s_mov_b32 s18, s96
	s_mov_b32 s64, s65
	s_mov_b32 s96, s15
	s_branch .LBB0_2477
